# split-K sample-row GEMM tails (G2,G4): residual loads issued before the K part, reduction LDS reads batched
# speedup vs baseline: 1.0076x; 1.0016x over previous
.LBB0_789:
	s_movk_i32 s22, 0x1400
	s_movk_i32 s23, 0x800
	s_and_b32 s2, s13, 0x70
	v_or_b32_e32 v5, s2, v12
	v_mul_u32_u24_e32 v6, 0xa00, v5
	s_and_b32 s6, s14, 0xffffffe0
	v_lshlrev_b32_e32 v194, 1, v6
	v_or_b32_e32 v6, s6, v12
	v_ashrrev_i32_e32 v7, 31, v6
	v_lshlrev_b64 v[8:9], 11, v[6:7]
	v_lshl_add_u64 v[34:35], v[2:3], 0, v[8:9]
	v_or_b32_e32 v14, 16, v6
	v_ashrrev_i32_e32 v15, 31, v14
	v_lshl_add_u64 v[10:11], v[0:1], 0, v[194:195]
	v_lshlrev_b64 v[14:15], 11, v[14:15]
	v_lshl_add_u64 v[36:37], v[2:3], 0, v[14:15]
	s_andn2_b64 vcc, exec, s[4:5]
	v_add_u32_e32 v10, s12, v13
	v_or_b32_e32 v94, 0x4000, v5
	v_lshlrev_b32_e32 v94, 11, v94
	v_mov_b32_e32 v95, 0
	v_lshl_add_u64 v[94:95], s[0:1], 0, v[94:95]
	v_mov_b32_e32 v96, s6
	v_mov_b32_e32 v97, 0
	v_lshl_add_u64 v[94:95], v[96:97], 1, v[94:95]
	v_mov_b32_e32 v96, v4
	v_lshl_add_u64 v[94:95], v[94:95], 0, v[96:97]
	global_load_dwordx2 v[90:91], v[94:95], off
	global_load_dwordx2 v[92:93], v[94:95], off offset:32
	v_mbcnt_lo_u32_b32 v40, -1, 0
	v_mbcnt_hi_u32_b32 v40, -1, v40
	v_lshrrev_b32_e32 v41, 2, v40
	v_lshrrev_b32_e32 v42, 4, v40
	v_and_b32_e32 v43, 3, v40
	v_xor_b32_e32 v43, v43, v42
	v_sub_u32_e32 v43, v43, v42
	v_lshlrev_b32_e32 v43, 4, v43
	s_and_b32 s56, s13, 0x70
	v_add_u32_e32 v44, s56, v41
	v_mad_u32_u24 v44, v44, s22, v43
	v_ashrrev_i32_e32 v45, 31, v44
	v_lshl_add_u64 v[44:45], v[0:1], 0, v[44:45]
	v_add_u32_e32 v46, s6, v41
	v_mad_u32_u24 v46, v46, s23, v43
	v_ashrrev_i32_e32 v47, 31, v46
	v_lshl_add_u64 v[46:47], v[2:3], 0, v[46:47]
	s_lshl_b32 s58, s23, 4
	s_mov_b32 s59, 0
	v_lshl_add_u64 v[48:49], v[46:47], 0, s[58:59]
	v_lshrrev_b32_e32 v50, 2, v12
	v_xor_b32_e32 v50, v50, v42
	v_lshlrev_b32_e32 v50, 4, v50
	v_lshl_or_b32 v50, v12, 6, v50
	s_mul_i32 s57, s89, 0x3000
	s_add_i32 s57, s57, 0x4000
	v_add_u32_e32 v50, s57, v50
	s_add_i32 m0, s57, 0
	s_nop 0
	global_load_lds_dwordx4 v[44:45], off
	s_add_i32 m0, s57, 1024
	s_nop 0
	global_load_lds_dwordx4 v[46:47], off
	s_add_i32 m0, s57, 2048
	s_nop 0
	global_load_lds_dwordx4 v[48:49], off
	s_add_i32 m0, s57, 3008
	s_nop 0
	global_load_lds_dwordx4 v[44:45], off offset:64
	s_add_i32 m0, s57, 4032
	s_nop 0
	global_load_lds_dwordx4 v[46:47], off offset:64
	s_add_i32 m0, s57, 5056
	s_nop 0
	global_load_lds_dwordx4 v[48:49], off offset:64
	s_add_i32 m0, s57, 6016
	s_nop 0
	global_load_lds_dwordx4 v[44:45], off offset:128
	s_add_i32 m0, s57, 7040
	s_nop 0
	global_load_lds_dwordx4 v[46:47], off offset:128
	s_add_i32 m0, s57, 8064
	s_nop 0
	global_load_lds_dwordx4 v[48:49], off offset:128
	s_add_i32 m0, s57, 9024
	s_nop 0
	global_load_lds_dwordx4 v[44:45], off offset:192
	s_add_i32 m0, s57, 10048
	s_nop 0
	global_load_lds_dwordx4 v[46:47], off offset:192
	s_add_i32 m0, s57, 11072
	s_nop 0
	global_load_lds_dwordx4 v[48:49], off offset:192
	s_waitcnt vmcnt(9)
	ds_read_b128 v[52:55], v50 offset:0
	ds_read_b128 v[56:59], v50 offset:1024
	ds_read_b128 v[60:63], v50 offset:2048
	s_waitcnt lgkmcnt(0)
	v_mfma_f32_16x16x32_bf16 v[6:9], v[56:59], v[52:55], 0
	v_mfma_f32_16x16x32_bf16 v[14:17], v[60:63], v[52:55], 0
	s_waitcnt vmcnt(6)
	ds_read_b128 v[64:67], v50 offset:3072
	ds_read_b128 v[68:71], v50 offset:4096
	ds_read_b128 v[72:75], v50 offset:5120
	s_waitcnt lgkmcnt(0)
	v_mfma_f32_16x16x32_bf16 v[6:9], v[68:71], v[64:67], v[6:9]
	v_mfma_f32_16x16x32_bf16 v[14:17], v[72:75], v[64:67], v[14:17]
	s_waitcnt vmcnt(3)
	ds_read_b128 v[52:55], v50 offset:6144
	ds_read_b128 v[56:59], v50 offset:7168
	ds_read_b128 v[60:63], v50 offset:8192
	s_waitcnt lgkmcnt(0)
	v_mfma_f32_16x16x32_bf16 v[6:9], v[56:59], v[52:55], v[6:9]
	v_mfma_f32_16x16x32_bf16 v[14:17], v[60:63], v[52:55], v[14:17]
	s_waitcnt vmcnt(0)
	ds_read_b128 v[64:67], v50 offset:9216
	ds_read_b128 v[68:71], v50 offset:10240
	ds_read_b128 v[72:75], v50 offset:11264
	s_waitcnt lgkmcnt(0)
	v_mfma_f32_16x16x32_bf16 v[6:9], v[68:71], v[64:67], v[6:9]
	v_mfma_f32_16x16x32_bf16 v[14:17], v[72:75], v[64:67], v[14:17]
	s_nop 6
	ds_write_b128 v10, v[6:9]
	ds_write_b128 v10, v[14:17] offset:16
	s_waitcnt lgkmcnt(0)
	s_barrier
	s_cbranch_vccnz .LBB0_788
	v_add_u32_e32 v24, 0, v13
	ds_read_b128 v[100:103], v24
	ds_read_b128 v[104:107], v24 offset:16
	ds_read_b128 v[108:111], v24 offset:2048
	ds_read_b128 v[112:115], v24 offset:2064
	ds_read_b128 v[116:119], v24 offset:4096
	ds_read_b128 v[120:123], v24 offset:4112
	ds_read_b128 v[124:127], v24 offset:6144
	ds_read_b128 v[128:131], v24 offset:6160
	ds_read_b128 v[132:135], v24 offset:8192
	ds_read_b128 v[136:139], v24 offset:8208
	ds_read_b128 v[140:143], v24 offset:10240
	ds_read_b128 v[144:147], v24 offset:10256
	ds_read_b128 v[148:151], v24 offset:12288
	ds_read_b128 v[152:155], v24 offset:12304
	ds_read_b128 v[156:159], v24 offset:14336
	ds_read_b128 v[160:163], v24 offset:14352
	s_ashr_i32 s7, s6, 31
	v_or_b32_e32 v14, 0x4000, v5
	v_lshlrev_b32_e32 v194, 11, v14
	s_waitcnt lgkmcnt(0)
	v_pk_add_f32 v[164:165], v[100:101], 0 op_sel_hi:[1,0]
	v_pk_add_f32 v[166:167], v[102:103], 0 op_sel_hi:[1,0]
	v_pk_add_f32 v[168:169], v[104:105], 0 op_sel_hi:[1,0]
	v_pk_add_f32 v[170:171], v[106:107], 0 op_sel_hi:[1,0]
	v_pk_add_f32 v[164:165], v[164:165], v[108:109]
	v_pk_add_f32 v[166:167], v[166:167], v[110:111]
	v_pk_add_f32 v[168:169], v[168:169], v[112:113]
	v_pk_add_f32 v[170:171], v[170:171], v[114:115]
	v_pk_add_f32 v[164:165], v[164:165], v[116:117]
	v_pk_add_f32 v[166:167], v[166:167], v[118:119]
	v_pk_add_f32 v[168:169], v[168:169], v[120:121]
	v_pk_add_f32 v[170:171], v[170:171], v[122:123]
	v_pk_add_f32 v[164:165], v[164:165], v[124:125]
	v_pk_add_f32 v[166:167], v[166:167], v[126:127]
	v_pk_add_f32 v[168:169], v[168:169], v[128:129]
	v_pk_add_f32 v[170:171], v[170:171], v[130:131]
	v_pk_add_f32 v[164:165], v[164:165], v[132:133]
	v_pk_add_f32 v[166:167], v[166:167], v[134:135]
	v_pk_add_f32 v[168:169], v[168:169], v[136:137]
	v_pk_add_f32 v[170:171], v[170:171], v[138:139]
	v_pk_add_f32 v[164:165], v[164:165], v[140:141]
	v_pk_add_f32 v[166:167], v[166:167], v[142:143]
	v_pk_add_f32 v[168:169], v[168:169], v[144:145]
	v_pk_add_f32 v[170:171], v[170:171], v[146:147]
	v_pk_add_f32 v[164:165], v[164:165], v[148:149]
	v_pk_add_f32 v[166:167], v[166:167], v[150:151]
	v_pk_add_f32 v[168:169], v[168:169], v[152:153]
	v_pk_add_f32 v[170:171], v[170:171], v[154:155]
	v_pk_add_f32 v[18:19], v[164:165], v[156:157]
	v_pk_add_f32 v[8:9], v[166:167], v[158:159]
	v_pk_add_f32 v[10:11], v[168:169], v[160:161]
	v_pk_add_f32 v[6:7], v[170:171], v[162:163]
	v_lshl_add_u64 v[16:17], s[0:1], 0, v[194:195]
	v_lshl_add_u64 v[16:17], s[6:7], 1, v[16:17]
	v_mov_b32_e32 v5, v195
	v_lshl_add_u64 v[16:17], v[16:17], 0, v[4:5]
	v_mov_b32_e32 v20, v90
	v_mov_b32_e32 v21, v91
	v_mov_b32_e32 v22, v92
	v_mov_b32_e32 v23, v93
	s_waitcnt vmcnt(0) lgkmcnt(0)
	v_lshlrev_b32_e32 v24, 16, v20
	v_and_b32_e32 v25, 0xffff0000, v20
	v_lshlrev_b32_e32 v20, 16, v21
	v_and_b32_e32 v21, 0xffff0000, v21
	v_pk_add_f32 v[18:19], v[18:19], v[24:25]
	v_pk_add_f32 v[8:9], v[8:9], v[20:21]
	v_cvt_pk_bf16_f32 v18, v18, v19
	v_cvt_pk_bf16_f32 v19, v8, v9
	v_lshlrev_b32_e32 v8, 16, v22
	v_and_b32_e32 v9, 0xffff0000, v22
	v_pk_add_f32 v[8:9], v[10:11], v[8:9]
	v_lshlrev_b32_e32 v10, 16, v23
	v_and_b32_e32 v11, 0xffff0000, v23
	v_pk_add_f32 v[6:7], v[6:7], v[10:11]
	v_cvt_pk_bf16_f32 v8, v8, v9
	v_cvt_pk_bf16_f32 v9, v6, v7
	v_and_b32_e32 v6, 0xffff0000, v18
	v_lshlrev_b32_e32 v5, 16, v18
	v_and_b32_e32 v10, 0xffff0000, v19
	v_mul_f32_e32 v6, v6, v6
	v_lshlrev_b32_e32 v7, 16, v19
	v_fmac_f32_e32 v6, v5, v5
	v_mul_f32_e32 v5, v10, v10
	global_store_dwordx2 v[16:17], v[18:19], off
	global_store_dwordx2 v[16:17], v[8:9], off offset:32
	v_lshlrev_b32_e32 v11, 16, v8
	v_and_b32_e32 v8, 0xffff0000, v8
	v_fmac_f32_e32 v5, v7, v7
	v_add_f32_e32 v5, v6, v5
	v_mul_f32_e32 v6, v8, v8
	v_lshlrev_b32_e32 v15, 16, v9
	v_and_b32_e32 v9, 0xffff0000, v9
	v_fmac_f32_e32 v6, v11, v11
	v_add_f32_e32 v5, v5, v6
	v_mul_f32_e32 v6, v9, v9
	v_fmac_f32_e32 v6, v15, v15
	v_and_b32_e32 v7, 64, v243
	v_add_f32_e32 v5, v6, v5
	v_xor_b32_e32 v6, 16, v243
	v_add_u32_e32 v7, 64, v7
	v_cmp_lt_i32_e32 vcc, v6, v7
	s_nop 1
	v_cndmask_b32_e32 v6, v243, v6, vcc
	v_lshlrev_b32_e32 v6, 2, v6
	ds_bpermute_b32 v6, v6, v5
	s_waitcnt lgkmcnt(0)
	v_add_f32_e32 v5, v5, v6
	v_xor_b32_e32 v6, 32, v243
	v_cmp_lt_i32_e32 vcc, v6, v7
	s_nop 1
	v_cndmask_b32_e32 v6, v243, v6, vcc
	v_lshlrev_b32_e32 v6, 2, v6
	ds_bpermute_b32 v6, v6, v5
	s_and_saveexec_b64 s[2:3], s[8:9]
	s_cbranch_execz .LBB0_787
	s_waitcnt lgkmcnt(0)
	v_add_f32_e32 v5, v5, v6
	s_mov_b32 s6, 0x4b800000
	v_fma_f32 v5, v5, s6, 0.5
	v_trunc_f32_e32 v5, v5
	v_mul_f32_e32 v6, 0x2f800000, v5
	v_floor_f32_e32 v7, v6
	v_fmac_f32_e32 v5, 0xcf800000, v7
	v_cvt_u32_f32_e32 v6, v5
	v_cvt_u32_f32_e32 v7, v7
	v_lshlrev_b32_e32 v194, 3, v14
	v_lshl_add_u64 v[8:9], s[10:11], 0, v[194:195]
	global_atomic_add_x2 v[8:9], v[6:7], off
	s_branch .LBB0_787

.LBB0_1088:
	s_and_b32 s10, s14, 0xffffffe0
	s_and_b32 s2, s13, 0x70
	v_or_b32_e32 v8, s10, v12
	s_movk_i32 s11, 0x1600
	v_or_b32_e32 v5, s2, v12
	v_mad_i64_i32 v[10:11], s[2:3], v8, s11, v[2:3]
	v_mul_u32_u24_e32 v6, 0xb00, v5
	v_or_b32_e32 v8, 16, v8
	v_lshlrev_b32_e32 v194, 1, v6
	v_mad_i64_i32 v[8:9], s[2:3], v8, s11, v[2:3]
	v_lshl_add_u64 v[6:7], v[0:1], 0, v[194:195]
	s_andn2_b64 vcc, exec, s[8:9]
	v_add_u32_e32 v30, s12, v13
	v_or_b32_e32 v94, 0x4000, v5
	v_lshlrev_b32_e32 v94, 11, v94
	v_mov_b32_e32 v95, 0
	v_lshl_add_u64 v[94:95], s[0:1], 0, v[94:95]
	v_mov_b32_e32 v96, s10
	v_mov_b32_e32 v97, 0
	v_lshl_add_u64 v[94:95], v[96:97], 1, v[94:95]
	v_mov_b32_e32 v96, v4
	v_lshl_add_u64 v[94:95], v[94:95], 0, v[96:97]
	global_load_dwordx2 v[90:91], v[94:95], off
	global_load_dwordx2 v[92:93], v[94:95], off offset:32
	v_mbcnt_lo_u32_b32 v40, -1, 0
	v_mbcnt_hi_u32_b32 v40, -1, v40
	v_lshrrev_b32_e32 v41, 2, v40
	v_lshrrev_b32_e32 v42, 4, v40
	v_and_b32_e32 v43, 3, v40
	v_xor_b32_e32 v43, v43, v42
	v_sub_u32_e32 v43, v43, v42
	v_lshlrev_b32_e32 v43, 4, v43
	s_and_b32 s16, s13, 0x70
	v_add_u32_e32 v44, s16, v41
	v_mad_u32_u24 v44, v44, s11, v43
	v_ashrrev_i32_e32 v45, 31, v44
	v_lshl_add_u64 v[44:45], v[0:1], 0, v[44:45]
	v_add_u32_e32 v46, s10, v41
	v_mad_u32_u24 v46, v46, s11, v43
	v_ashrrev_i32_e32 v47, 31, v46
	v_lshl_add_u64 v[46:47], v[2:3], 0, v[46:47]
	s_lshl_b32 s18, s11, 4
	s_mov_b32 s19, 0
	v_lshl_add_u64 v[48:49], v[46:47], 0, s[18:19]
	v_lshrrev_b32_e32 v50, 2, v12
	v_xor_b32_e32 v50, v50, v42
	v_lshlrev_b32_e32 v50, 4, v50
	v_lshl_or_b32 v50, v12, 6, v50
	s_mul_i32 s17, s89, 0x3000
	s_add_i32 s17, s17, 0x4000
	v_add_u32_e32 v50, s17, v50
	s_add_i32 m0, s17, 0
	s_nop 0
	global_load_lds_dwordx4 v[44:45], off
	s_add_i32 m0, s17, 1024
	s_nop 0
	global_load_lds_dwordx4 v[46:47], off
	s_add_i32 m0, s17, 2048
	s_nop 0
	global_load_lds_dwordx4 v[48:49], off
	s_add_i32 m0, s17, 3008
	s_nop 0
	global_load_lds_dwordx4 v[44:45], off offset:64
	s_add_i32 m0, s17, 4032
	s_nop 0
	global_load_lds_dwordx4 v[46:47], off offset:64
	s_add_i32 m0, s17, 5056
	s_nop 0
	global_load_lds_dwordx4 v[48:49], off offset:64
	s_add_i32 m0, s17, 6016
	s_nop 0
	global_load_lds_dwordx4 v[44:45], off offset:128
	s_add_i32 m0, s17, 7040
	s_nop 0
	global_load_lds_dwordx4 v[46:47], off offset:128
	s_add_i32 m0, s17, 8064
	s_nop 0
	global_load_lds_dwordx4 v[48:49], off offset:128
	s_add_i32 m0, s17, 9024
	s_nop 0
	global_load_lds_dwordx4 v[44:45], off offset:192
	s_add_i32 m0, s17, 10048
	s_nop 0
	global_load_lds_dwordx4 v[46:47], off offset:192
	s_add_i32 m0, s17, 11072
	s_nop 0
	global_load_lds_dwordx4 v[48:49], off offset:192
	s_waitcnt vmcnt(9)
	ds_read_b128 v[52:55], v50 offset:0
	ds_read_b128 v[56:59], v50 offset:1024
	ds_read_b128 v[60:63], v50 offset:2048
	s_waitcnt lgkmcnt(0)
	s_sub_i32 m0, s17, 256
	s_nop 0
	global_load_lds_dwordx4 v[44:45], off offset:256
	s_add_i32 m0, s17, 768
	s_nop 0
	global_load_lds_dwordx4 v[46:47], off offset:256
	s_add_i32 m0, s17, 1792
	s_nop 0
	global_load_lds_dwordx4 v[48:49], off offset:256
	v_mfma_f32_16x16x32_bf16 v[14:17], v[56:59], v[52:55], 0
	v_mfma_f32_16x16x32_bf16 v[6:9], v[60:63], v[52:55], 0
	s_waitcnt vmcnt(9)
	ds_read_b128 v[64:67], v50 offset:3072
	ds_read_b128 v[68:71], v50 offset:4096
	ds_read_b128 v[72:75], v50 offset:5120
	s_waitcnt lgkmcnt(0)
	s_add_i32 m0, s17, 2752
	s_nop 0
	global_load_lds_dwordx4 v[44:45], off offset:320
	s_add_i32 m0, s17, 3776
	s_nop 0
	global_load_lds_dwordx4 v[46:47], off offset:320
	s_add_i32 m0, s17, 4800
	s_nop 0
	global_load_lds_dwordx4 v[48:49], off offset:320
	v_mfma_f32_16x16x32_bf16 v[14:17], v[68:71], v[64:67], v[14:17]
	v_mfma_f32_16x16x32_bf16 v[6:9], v[72:75], v[64:67], v[6:9]
	s_waitcnt vmcnt(9)
	ds_read_b128 v[52:55], v50 offset:6144
	ds_read_b128 v[56:59], v50 offset:7168
	ds_read_b128 v[60:63], v50 offset:8192
	s_waitcnt lgkmcnt(0)
	s_add_i32 m0, s17, 5760
	s_nop 0
	global_load_lds_dwordx4 v[44:45], off offset:384
	s_add_i32 m0, s17, 6784
	s_nop 0
	global_load_lds_dwordx4 v[46:47], off offset:384
	s_add_i32 m0, s17, 7808
	s_nop 0
	global_load_lds_dwordx4 v[48:49], off offset:384
	v_mfma_f32_16x16x32_bf16 v[14:17], v[56:59], v[52:55], v[14:17]
	v_mfma_f32_16x16x32_bf16 v[6:9], v[60:63], v[52:55], v[6:9]
	s_waitcnt vmcnt(9)
	ds_read_b128 v[64:67], v50 offset:9216
	ds_read_b128 v[68:71], v50 offset:10240
	ds_read_b128 v[72:75], v50 offset:11264
	s_waitcnt lgkmcnt(0)
	s_add_i32 m0, s17, 8768
	s_nop 0
	global_load_lds_dwordx4 v[44:45], off offset:448
	s_add_i32 m0, s17, 9792
	s_nop 0
	global_load_lds_dwordx4 v[46:47], off offset:448
	s_add_i32 m0, s17, 10816
	s_nop 0
	global_load_lds_dwordx4 v[48:49], off offset:448
	v_mfma_f32_16x16x32_bf16 v[14:17], v[68:71], v[64:67], v[14:17]
	v_mfma_f32_16x16x32_bf16 v[6:9], v[72:75], v[64:67], v[6:9]
	s_waitcnt vmcnt(9)
	ds_read_b128 v[52:55], v50 offset:0
	ds_read_b128 v[56:59], v50 offset:1024
	ds_read_b128 v[60:63], v50 offset:2048
	s_waitcnt lgkmcnt(0)
	s_sub_i32 m0, s17, 512
	s_nop 0
	global_load_lds_dwordx4 v[44:45], off offset:512
	s_add_i32 m0, s17, 512
	s_nop 0
	global_load_lds_dwordx4 v[46:47], off offset:512
	s_add_i32 m0, s17, 1536
	s_nop 0
	global_load_lds_dwordx4 v[48:49], off offset:512
	v_mfma_f32_16x16x32_bf16 v[14:17], v[56:59], v[52:55], v[14:17]
	v_mfma_f32_16x16x32_bf16 v[6:9], v[60:63], v[52:55], v[6:9]
	s_waitcnt vmcnt(9)
	ds_read_b128 v[64:67], v50 offset:3072
	ds_read_b128 v[68:71], v50 offset:4096
	ds_read_b128 v[72:75], v50 offset:5120
	s_waitcnt lgkmcnt(0)
	s_add_i32 m0, s17, 2496
	s_nop 0
	global_load_lds_dwordx4 v[44:45], off offset:576
	s_add_i32 m0, s17, 3520
	s_nop 0
	global_load_lds_dwordx4 v[46:47], off offset:576
	s_add_i32 m0, s17, 4544
	s_nop 0
	global_load_lds_dwordx4 v[48:49], off offset:576
	v_mfma_f32_16x16x32_bf16 v[14:17], v[68:71], v[64:67], v[14:17]
	v_mfma_f32_16x16x32_bf16 v[6:9], v[72:75], v[64:67], v[6:9]
	s_waitcnt vmcnt(9)
	ds_read_b128 v[52:55], v50 offset:6144
	ds_read_b128 v[56:59], v50 offset:7168
	ds_read_b128 v[60:63], v50 offset:8192
	s_waitcnt lgkmcnt(0)
	s_add_i32 m0, s17, 5504
	s_nop 0
	global_load_lds_dwordx4 v[44:45], off offset:640
	s_add_i32 m0, s17, 6528
	s_nop 0
	global_load_lds_dwordx4 v[46:47], off offset:640
	s_add_i32 m0, s17, 7552
	s_nop 0
	global_load_lds_dwordx4 v[48:49], off offset:640
	v_mfma_f32_16x16x32_bf16 v[14:17], v[56:59], v[52:55], v[14:17]
	v_mfma_f32_16x16x32_bf16 v[6:9], v[60:63], v[52:55], v[6:9]
	s_waitcnt vmcnt(9)
	ds_read_b128 v[64:67], v50 offset:9216
	ds_read_b128 v[68:71], v50 offset:10240
	ds_read_b128 v[72:75], v50 offset:11264
	s_waitcnt lgkmcnt(0)
	v_mfma_f32_16x16x32_bf16 v[14:17], v[68:71], v[64:67], v[14:17]
	v_mfma_f32_16x16x32_bf16 v[6:9], v[72:75], v[64:67], v[6:9]
	s_waitcnt vmcnt(6)
	ds_read_b128 v[52:55], v50 offset:0
	ds_read_b128 v[56:59], v50 offset:1024
	ds_read_b128 v[60:63], v50 offset:2048
	s_waitcnt lgkmcnt(0)
	v_mfma_f32_16x16x32_bf16 v[14:17], v[56:59], v[52:55], v[14:17]
	v_mfma_f32_16x16x32_bf16 v[6:9], v[60:63], v[52:55], v[6:9]
	s_waitcnt vmcnt(3)
	ds_read_b128 v[64:67], v50 offset:3072
	ds_read_b128 v[68:71], v50 offset:4096
	ds_read_b128 v[72:75], v50 offset:5120
	s_waitcnt lgkmcnt(0)
	v_mfma_f32_16x16x32_bf16 v[14:17], v[68:71], v[64:67], v[14:17]
	v_mfma_f32_16x16x32_bf16 v[6:9], v[72:75], v[64:67], v[6:9]
	s_waitcnt vmcnt(0)
	ds_read_b128 v[52:55], v50 offset:6144
	ds_read_b128 v[56:59], v50 offset:7168
	ds_read_b128 v[60:63], v50 offset:8192
	s_waitcnt lgkmcnt(0)
	v_mfma_f32_16x16x32_bf16 v[14:17], v[56:59], v[52:55], v[14:17]
	v_mfma_f32_16x16x32_bf16 v[6:9], v[60:63], v[52:55], v[6:9]
	s_nop 6
	ds_write_b128 v30, v[14:17]
	ds_write_b128 v30, v[6:9] offset:16
	s_waitcnt lgkmcnt(0)
	s_barrier
	s_cbranch_vccnz .LBB0_1087
	v_add_u32_e32 v24, 0, v13
	ds_read_b128 v[100:103], v24
	ds_read_b128 v[104:107], v24 offset:16
	ds_read_b128 v[108:111], v24 offset:2048
	ds_read_b128 v[112:115], v24 offset:2064
	ds_read_b128 v[116:119], v24 offset:4096
	ds_read_b128 v[120:123], v24 offset:4112
	ds_read_b128 v[124:127], v24 offset:6144
	ds_read_b128 v[128:131], v24 offset:6160
	ds_read_b128 v[132:135], v24 offset:8192
	ds_read_b128 v[136:139], v24 offset:8208
	ds_read_b128 v[140:143], v24 offset:10240
	ds_read_b128 v[144:147], v24 offset:10256
	ds_read_b128 v[148:151], v24 offset:12288
	ds_read_b128 v[152:155], v24 offset:12304
	ds_read_b128 v[156:159], v24 offset:14336
	ds_read_b128 v[160:163], v24 offset:14352
	s_ashr_i32 s11, s10, 31
	v_or_b32_e32 v14, 0x4000, v5
	v_lshlrev_b32_e32 v194, 11, v14
	s_waitcnt lgkmcnt(0)
	v_pk_add_f32 v[164:165], v[100:101], 0 op_sel_hi:[1,0]
	v_pk_add_f32 v[166:167], v[102:103], 0 op_sel_hi:[1,0]
	v_pk_add_f32 v[168:169], v[104:105], 0 op_sel_hi:[1,0]
	v_pk_add_f32 v[170:171], v[106:107], 0 op_sel_hi:[1,0]
	v_pk_add_f32 v[164:165], v[164:165], v[108:109]
	v_pk_add_f32 v[166:167], v[166:167], v[110:111]
	v_pk_add_f32 v[168:169], v[168:169], v[112:113]
	v_pk_add_f32 v[170:171], v[170:171], v[114:115]
	v_pk_add_f32 v[164:165], v[164:165], v[116:117]
	v_pk_add_f32 v[166:167], v[166:167], v[118:119]
	v_pk_add_f32 v[168:169], v[168:169], v[120:121]
	v_pk_add_f32 v[170:171], v[170:171], v[122:123]
	v_pk_add_f32 v[164:165], v[164:165], v[124:125]
	v_pk_add_f32 v[166:167], v[166:167], v[126:127]
	v_pk_add_f32 v[168:169], v[168:169], v[128:129]
	v_pk_add_f32 v[170:171], v[170:171], v[130:131]
	v_pk_add_f32 v[164:165], v[164:165], v[132:133]
	v_pk_add_f32 v[166:167], v[166:167], v[134:135]
	v_pk_add_f32 v[168:169], v[168:169], v[136:137]
	v_pk_add_f32 v[170:171], v[170:171], v[138:139]
	v_pk_add_f32 v[164:165], v[164:165], v[140:141]
	v_pk_add_f32 v[166:167], v[166:167], v[142:143]
	v_pk_add_f32 v[168:169], v[168:169], v[144:145]
	v_pk_add_f32 v[170:171], v[170:171], v[146:147]
	v_pk_add_f32 v[164:165], v[164:165], v[148:149]
	v_pk_add_f32 v[166:167], v[166:167], v[150:151]
	v_pk_add_f32 v[168:169], v[168:169], v[152:153]
	v_pk_add_f32 v[170:171], v[170:171], v[154:155]
	v_pk_add_f32 v[18:19], v[164:165], v[156:157]
	v_pk_add_f32 v[8:9], v[166:167], v[158:159]
	v_pk_add_f32 v[10:11], v[168:169], v[160:161]
	v_pk_add_f32 v[6:7], v[170:171], v[162:163]
	v_lshl_add_u64 v[16:17], s[0:1], 0, v[194:195]
	v_lshl_add_u64 v[16:17], s[10:11], 1, v[16:17]
	v_mov_b32_e32 v5, v195
	v_lshl_add_u64 v[16:17], v[16:17], 0, v[4:5]
	v_mov_b32_e32 v20, v90
	v_mov_b32_e32 v21, v91
	v_mov_b32_e32 v22, v92
	v_mov_b32_e32 v23, v93
	s_waitcnt vmcnt(0) lgkmcnt(0)
	v_lshlrev_b32_e32 v24, 16, v20
	v_and_b32_e32 v25, 0xffff0000, v20
	v_lshlrev_b32_e32 v20, 16, v21
	v_and_b32_e32 v21, 0xffff0000, v21
	v_pk_add_f32 v[18:19], v[18:19], v[24:25]
	v_pk_add_f32 v[8:9], v[8:9], v[20:21]
	v_cvt_pk_bf16_f32 v18, v18, v19
	v_cvt_pk_bf16_f32 v19, v8, v9
	v_lshlrev_b32_e32 v8, 16, v22
	v_and_b32_e32 v9, 0xffff0000, v22
	v_pk_add_f32 v[8:9], v[10:11], v[8:9]
	v_lshlrev_b32_e32 v10, 16, v23
	v_and_b32_e32 v11, 0xffff0000, v23
	v_pk_add_f32 v[6:7], v[6:7], v[10:11]
	v_cvt_pk_bf16_f32 v8, v8, v9
	v_cvt_pk_bf16_f32 v9, v6, v7
	v_and_b32_e32 v6, 0xffff0000, v18
	v_lshlrev_b32_e32 v5, 16, v18
	v_and_b32_e32 v10, 0xffff0000, v19
	v_mul_f32_e32 v6, v6, v6
	v_lshlrev_b32_e32 v7, 16, v19
	v_fmac_f32_e32 v6, v5, v5
	v_mul_f32_e32 v5, v10, v10
	global_store_dwordx2 v[16:17], v[18:19], off
	global_store_dwordx2 v[16:17], v[8:9], off offset:32
	v_lshlrev_b32_e32 v11, 16, v8
	v_and_b32_e32 v8, 0xffff0000, v8
	v_fmac_f32_e32 v5, v7, v7
	v_add_f32_e32 v5, v6, v5
	v_mul_f32_e32 v6, v8, v8
	v_lshlrev_b32_e32 v15, 16, v9
	v_and_b32_e32 v9, 0xffff0000, v9
	v_fmac_f32_e32 v6, v11, v11
	v_add_f32_e32 v5, v5, v6
	v_mul_f32_e32 v6, v9, v9
	v_fmac_f32_e32 v6, v15, v15
	v_and_b32_e32 v7, 64, v243
	v_add_f32_e32 v5, v6, v5
	v_xor_b32_e32 v6, 16, v243
	v_add_u32_e32 v7, 64, v7
	v_cmp_lt_i32_e32 vcc, v6, v7
	s_nop 1
	v_cndmask_b32_e32 v6, v243, v6, vcc
	v_lshlrev_b32_e32 v6, 2, v6
	ds_bpermute_b32 v6, v6, v5
	s_waitcnt lgkmcnt(0)
	v_add_f32_e32 v5, v5, v6
	v_xor_b32_e32 v6, 32, v243
	v_cmp_lt_i32_e32 vcc, v6, v7
	s_nop 1
	v_cndmask_b32_e32 v6, v243, v6, vcc
	v_lshlrev_b32_e32 v6, 2, v6
	ds_bpermute_b32 v6, v6, v5
	s_and_saveexec_b64 s[2:3], s[4:5]
	s_cbranch_execz .LBB0_1086
	s_waitcnt lgkmcnt(0)
	v_add_f32_e32 v5, v5, v6
	s_mov_b32 s10, 0x4b800000
	v_fma_f32 v5, v5, s10, 0.5
	v_trunc_f32_e32 v5, v5
	v_mul_f32_e32 v6, 0x2f800000, v5
	v_floor_f32_e32 v7, v6
	v_fmac_f32_e32 v5, 0xcf800000, v7
	v_cvt_u32_f32_e32 v6, v5
	v_cvt_u32_f32_e32 v7, v7
	v_lshlrev_b32_e32 v194, 3, v14
	v_lshl_add_u64 v[8:9], s[6:7], 0, v[194:195]
	global_atomic_add_x2 v[8:9], v[6:7], off
	s_branch .LBB0_1086
